# grid barrier: acquire-side buffer_inv sc1 issued by thread 0 right after its arrival atomic (before polling) instead of after observing the release; nothing but sc1 polls runs in between
# speedup vs baseline: 1.0099x; 1.0021x over previous
; __device__ __forceinline__ unsigned xb_ld(unsigned* p)              { return __hip_atomic_load(p, __ATOMIC_RELAXED, __HIP_MEMORY_SCOPE_AGENT); }
; __device__ __forceinline__ unsigned xb_add(unsigned* p, unsigned v) { return __hip_atomic_fetch_add(p, v, __ATOMIC_RELAXED, __HIP_MEMORY_SCOPE_AGENT); }
; #define XB_SPIN(cond, bar) do { unsigned _sp = 0; while (cond) { __builtin_amdgcn_s_sleep(1); \
;     if ((++_sp & 255u) == 0u) { if (xb_ld(&(bar)[XB_TMO])) break; if (_sp > XB_SPIN_CAP) { atomicAdd(&(bar)[XB_TMO], 1u); break; } } } } while (0)
; __device__ __forceinline__ void xcd_barrier(const XcdBarrier& b, int tid_) {
;     ...
;         const unsigned old = xb_add(&bar[XB_XSUB(b.x)], 1u);
;         const unsigned gen = old / nloc;
;         if (old + 1u == (gen + 1u) * nloc) {
;             __builtin_amdgcn_fence(__ATOMIC_RELEASE, "agent");
;             asm volatile("s_waitcnt vmcnt(0)" ::: "memory");
;             const unsigned og = xb_add(&bar[XB_TOP], 1u);
;             const unsigned tg = og / nx;
;             if (og + 1u == (tg + 1u) * nx) xb_add(&bar[XB_TOPGEN], 1u);
;             else XB_SPIN(xb_ld(&bar[XB_TOPGEN]) == tg, bar);
;             __builtin_amdgcn_fence(__ATOMIC_ACQUIRE, "agent");
;             xb_add(&bar[XB_XGEN(b.x)], 1u);
;             asm volatile("s_waitcnt vmcnt(0)" ::: "memory");
;         } else {
;             XB_SPIN(xb_ld(&bar[XB_XGEN(b.x)]) == gen, bar);
;             __builtin_amdgcn_fence(__ATOMIC_ACQUIRE, "agent");
;             asm volatile("s_waitcnt vmcnt(0)" ::: "memory");
;         }
.LBB0_980:
	s_or_b64 exec, exec, s[4:5]
	v_cvt_f32_u32_e32 v5, v3
	s_waitcnt vmcnt(0)
	buffer_inv sc1
	v_readfirstlane_b32 s2, v4
	v_sub_u32_e32 v4, 0, v3
	v_rcp_iflag_f32_e32 v5, v5
	v_add_u32_e32 v6, s2, v0
	v_mul_f32_e32 v5, 0x4f7ffffe, v5
	v_cvt_u32_f32_e32 v5, v5
	v_mul_lo_u32 v0, v4, v5
	v_mul_hi_u32 v0, v5, v0
	v_add_u32_e32 v0, v5, v0
	v_mul_hi_u32 v0, v6, v0
	v_mul_lo_u32 v4, v0, v3
	v_sub_u32_e32 v4, v6, v4
	v_add_u32_e32 v5, 1, v0
	v_cmp_ge_u32_e32 vcc, v4, v3
	s_nop 1
	v_cndmask_b32_e32 v0, v0, v5, vcc
	v_sub_u32_e32 v5, v4, v3
	v_cndmask_b32_e32 v4, v4, v5, vcc
	v_add_u32_e32 v5, 1, v0
	v_cmp_ge_u32_e32 vcc, v4, v3
	v_add_u32_e32 v4, 1, v6
	s_nop 0
	v_cndmask_b32_e32 v0, v0, v5, vcc
	v_mul_lo_u32 v5, v3, v0
	v_add_u32_e32 v3, v5, v3
	v_cmp_ne_u32_e32 vcc, v4, v3
	s_and_saveexec_b64 s[4:5], vcc
	s_xor_b64 s[4:5], exec, s[4:5]
	s_cbranch_execz .LBB0_994
	v_readlane_b32 s6, v254, 2
	v_readlane_b32 s7, v254, 3
	s_waitcnt lgkmcnt(0)
	s_nop 3
	global_load_dword v2, v1, s[6:7] sc1
	s_waitcnt vmcnt(0)
	v_cmp_eq_u32_e32 vcc, v2, v0
	s_and_saveexec_b64 s[6:7], vcc
	s_cbranch_execz .LBB0_993
	s_mov_b32 s2, 1
	s_mov_b64 s[8:9], 0
	s_branch .LBB0_984

; __device__ __forceinline__ unsigned xb_ld(unsigned* p)              { return __hip_atomic_load(p, __ATOMIC_RELAXED, __HIP_MEMORY_SCOPE_AGENT); }
; __device__ __forceinline__ unsigned xb_add(unsigned* p, unsigned v) { return __hip_atomic_fetch_add(p, v, __ATOMIC_RELAXED, __HIP_MEMORY_SCOPE_AGENT); }
; #define XB_SPIN(cond, bar) do { unsigned _sp = 0; while (cond) { __builtin_amdgcn_s_sleep(1); \
;     if ((++_sp & 255u) == 0u) { if (xb_ld(&(bar)[XB_TMO])) break; if (_sp > XB_SPIN_CAP) { atomicAdd(&(bar)[XB_TMO], 1u); break; } } } } while (0)
; __device__ __forceinline__ void xcd_barrier(const XcdBarrier& b, int tid_) {
;     ...
;         if (old + 1u == (gen + 1u) * nloc) {
;             __builtin_amdgcn_fence(__ATOMIC_RELEASE, "agent");
;             asm volatile("s_waitcnt vmcnt(0)" ::: "memory");
;             const unsigned og = xb_add(&bar[XB_TOP], 1u);
;             const unsigned tg = og / nx;
;             if (og + 1u == (tg + 1u) * nx) xb_add(&bar[XB_TOPGEN], 1u);
;             else XB_SPIN(xb_ld(&bar[XB_TOPGEN]) == tg, bar);
;             __builtin_amdgcn_fence(__ATOMIC_ACQUIRE, "agent");
;             xb_add(&bar[XB_XGEN(b.x)], 1u);
;             asm volatile("s_waitcnt vmcnt(0)" ::: "memory");
;         } else {
;             XB_SPIN(xb_ld(&bar[XB_XGEN(b.x)]) == gen, bar);
;             __builtin_amdgcn_fence(__ATOMIC_ACQUIRE, "agent");
;             asm volatile("s_waitcnt vmcnt(0)" ::: "memory");
;         }
.LBB0_993:
	s_or_b64 exec, exec, s[6:7]
	s_waitcnt vmcnt(0)
.LBB0_994:
	s_andn2_saveexec_b64 s[4:5], s[4:5]
	s_cbranch_execz .Ltramp_b17
	s_mov_b64 s[4:5], exec
	buffer_wbl2 sc1
	s_waitcnt lgkmcnt(0)
	s_waitcnt vmcnt(0)
	v_mbcnt_lo_u32_b32 v0, s4, 0
	v_mbcnt_hi_u32_b32 v0, s5, v0
	v_cmp_eq_u32_e32 vcc, 0, v0
	s_and_saveexec_b64 s[6:7], vcc
	s_cbranch_execz .LBB0_997
	s_bcnt1_i32_b64 s2, s[4:5]
	v_readlane_b32 s4, v254, 4
	v_mov_b32_e32 v3, s2
	v_readlane_b32 s5, v254, 5
	s_nop 4
	global_atomic_add v3, v1, v3, s[4:5] sc0

; __device__ __forceinline__ unsigned xb_ld(unsigned* p)              { return __hip_atomic_load(p, __ATOMIC_RELAXED, __HIP_MEMORY_SCOPE_AGENT); }
; __device__ __forceinline__ unsigned xb_add(unsigned* p, unsigned v) { return __hip_atomic_fetch_add(p, v, __ATOMIC_RELAXED, __HIP_MEMORY_SCOPE_AGENT); }
; #define XB_SPIN(cond, bar) do { unsigned _sp = 0; while (cond) { __builtin_amdgcn_s_sleep(1); \
;     if ((++_sp & 255u) == 0u) { if (xb_ld(&(bar)[XB_TMO])) break; if (_sp > XB_SPIN_CAP) { atomicAdd(&(bar)[XB_TMO], 1u); break; } } } } while (0)
; __device__ __forceinline__ void xcd_barrier(const XcdBarrier& b, int tid_) {
;     ...
;             const unsigned og = xb_add(&bar[XB_TOP], 1u);
;             const unsigned tg = og / nx;
;             if (og + 1u == (tg + 1u) * nx) xb_add(&bar[XB_TOPGEN], 1u);
;             else XB_SPIN(xb_ld(&bar[XB_TOPGEN]) == tg, bar);
;             __builtin_amdgcn_fence(__ATOMIC_ACQUIRE, "agent");
;             xb_add(&bar[XB_XGEN(b.x)], 1u);
;             asm volatile("s_waitcnt vmcnt(0)" ::: "memory");
.LBB0_1011:
	s_or_b64 exec, exec, s[4:5]
	s_mov_b64 s[4:5], exec
	v_mbcnt_lo_u32_b32 v0, s4, 0
	v_mbcnt_hi_u32_b32 v0, s5, v0
	v_cmp_eq_u32_e32 vcc, 0, v0
	s_waitcnt vmcnt(0)
	s_and_saveexec_b64 s[6:7], vcc
	s_cbranch_execz .Ltramp_b16
	s_bcnt1_i32_b64 s2, s[4:5]
	v_readlane_b32 s4, v254, 2
	v_mov_b32_e32 v0, s2
	v_readlane_b32 s5, v254, 3
	s_nop 4
	global_atomic_add v1, v0, s[4:5]
	s_branch .Ltramp_b16
